# combined input projection: next tile's first two K stages requested behind this tile's K loop (before its epilogue); own operand addressing in the main K loop
# baseline (speedup 1.0000x reference)
.LBB0_256:
	s_cbranch_execz .LBB0_371
	v_readlane_b32 s0, v215, 49
	v_readlane_b32 s1, v215, 50
	s_andn2_b64 vcc, exec, s[0:1]
	s_cbranch_vccnz .LBB0_318
	v_readlane_b32 s0, v214, 57
	v_readlane_b32 s1, v214, 58
	s_mov_b32 s2, s0
	s_mul_hi_i32 s1, s0, 0x3500000
	s_mul_i32 s0, s0, 0x3500000
	s_lshl_b32 s12, s2, 4
	s_lshl_b32 s13, s2, 1
	s_add_u32 s2, s48, s0
	s_addc_u32 s3, s49, s1
	s_add_u32 s14, s2, 0x1064e000
	s_addc_u32 s15, s3, 0
	v_readlane_b32 s2, v214, 26
	s_add_u32 s0, s2, s0
	v_readlane_b32 s2, v214, 27
	s_addc_u32 s1, s2, s1
	v_readlane_b32 s16, v214, 12
	s_mov_b32 s70, 0
	v_writelane_b32 v243, s70, 2
	s_branch .LBB0_260

.LBB0_276:
	v_mov_b32_e32 v0, v142
	v_mov_b32_e32 v2, v142
	s_lshl_b32 s2, s17, 8
	v_lshlrev_b32_e32 v5, 7, v2
	v_lshlrev_b32_e32 v4, 6, v2
	v_and_b32_e32 v31, 0x2000, v5
	v_lshlrev_b32_e32 v5, 2, v2
	v_and_b32_e32 v3, 48, v2
	v_and_b32_e32 v30, 0xffffe000, v4
	v_and_b32_e32 v4, 0x3c0, v4
	v_and_b32_e32 v5, 32, v5
	v_bitop3_b32 v32, v4, v5, v3 bitop3:0x36
	v_ashrrev_i32_e32 v3, 31, v2
	v_lshrrev_b32_e32 v3, 26, v3
	v_lshlrev_b32_e32 v33, 4, v2
	v_add_u32_e32 v3, v2, v3
	v_bfe_i32 v2, v2, 27, 1
	v_lshrrev_b32_e32 v2, 22, v2
	v_add_u32_e32 v2, v33, v2
	v_and_b32_e32 v2, 0xfffffc00, v2
	v_sub_u32_e32 v2, v33, v2
	v_lshrrev_b32_e32 v4, 4, v2
	v_bitop3_b32 v4, v4, v2, 32 bitop3:0x6c
	v_ashrrev_i32_e32 v2, 31, v2
	v_ashrrev_i32_e32 v3, 6, v3
	v_lshrrev_b32_e32 v2, 26, v2
	v_lshlrev_b32_e32 v5, 3, v3
	v_add_u32_e32 v2, v4, v2
	v_and_b32_e32 v5, -16, v5
	v_ashrrev_i32_e32 v6, 6, v2
	v_add_u32_e32 v2, v6, v5
	v_mul_i32_i24_e32 v5, 64, v6
	s_ashr_i32 s3, s2, 31
	v_lshlrev_b32_e32 v3, 5, v3
	v_sub_u32_e32 v4, v4, v5
	s_lshl_b32 s40, s18, 7
	s_lshl_b64 s[4:5], s[2:3], 11
	v_and_b32_e32 v3, 32, v3
	v_ashrrev_i16_sdwa v4, v146, sext(v4) dst_sel:DWORD dst_unused:UNUSED_PAD src0_sel:DWORD src1_sel:BYTE_0
	s_add_u32 s10, s24, s4
	v_add_u32_sdwa v4, v3, sext(v4) dst_sel:DWORD dst_unused:UNUSED_PAD src0_sel:DWORD src1_sel:WORD_0
	v_ashrrev_i32_e32 v3, 31, v2
	s_addc_u32 s11, s25, s5
	v_lshlrev_b64 v[2:3], 11, v[2:3]
	v_ashrrev_i32_e32 v5, 31, v4
	v_add_u32_e32 v78, 0, v33
	v_add_u32_e32 v34, 0x2000, v33
	v_lshl_add_u64 v[6:7], s[10:11], 0, v[2:3]
	v_lshlrev_b64 v[4:5], 1, v[4:5]
	v_readfirstlane_b32 s19, v78
	v_ashrrev_i32_e32 v8, 31, v34
	v_add_u32_e32 v14, 0x2000, v78
	v_add_u32_e32 v35, 0x4000, v33
	v_lshl_add_u64 v[6:7], v[6:7], 0, v[4:5]
	s_mov_b32 m0, s19
	v_lshrrev_b32_e32 v8, 22, v8
	v_readfirstlane_b32 s19, v14
	v_ashrrev_i32_e32 v14, 31, v35
	v_add_u32_e32 v20, 0x4000, v78
	v_add_u32_e32 v36, 0x6000, v33
	s_waitcnt lgkmcnt(0)
	s_barrier
	v_add_u32_e32 v8, v34, v8
	s_mov_b32 m0, s19
	v_lshrrev_b32_e32 v14, 22, v14
	v_readfirstlane_b32 s19, v20
	v_ashrrev_i32_e32 v20, 31, v36
	v_ashrrev_i32_e32 v9, 10, v8
	v_add_u32_e32 v14, v35, v14
	v_lshrrev_b32_e32 v20, 22, v20
	v_mul_i32_i24_e32 v8, 0x400, v9
	v_ashrrev_i32_e32 v15, 10, v14
	v_add_u32_e32 v20, v36, v20
	v_sub_u32_e32 v8, v34, v8
	v_mul_i32_i24_e32 v14, 0x400, v15
	v_ashrrev_i32_e32 v21, 10, v20
	v_lshrrev_b32_e32 v10, 4, v8
	v_sub_u32_e32 v14, v35, v14
	v_mul_i32_i24_e32 v20, 0x400, v21
	v_bitop3_b32 v10, v10, v8, 32 bitop3:0x6c
	v_lshrrev_b32_e32 v16, 4, v14
	v_sub_u32_e32 v20, v36, v20
	v_ashrrev_i32_e32 v11, 31, v10
	v_bitop3_b32 v16, v16, v14, 32 bitop3:0x6c
	v_lshrrev_b32_e32 v22, 4, v20
	v_lshrrev_b32_e32 v11, 26, v11
	v_ashrrev_i32_e32 v17, 31, v16
	v_bitop3_b32 v22, v22, v20, 32 bitop3:0x6c
	v_add_u32_e32 v11, v10, v11
	v_lshrrev_b32_e32 v17, 26, v17
	v_ashrrev_i32_e32 v23, 31, v22
	v_lshlrev_b32_e32 v8, 3, v9
	v_ashrrev_i32_e32 v12, 6, v11
	v_and_b32_e32 v11, 0xc0, v11
	v_add_u32_e32 v17, v16, v17
	v_lshrrev_b32_e32 v23, 26, v23
	v_and_b32_e32 v8, -16, v8
	v_lshlrev_b32_e32 v9, 5, v9
	v_sub_u32_e32 v10, v10, v11
	v_lshlrev_b32_e32 v14, 3, v15
	v_ashrrev_i32_e32 v18, 6, v17
	v_and_b32_e32 v17, 0xc0, v17
	v_add_u32_e32 v23, v22, v23
	v_add_u32_e32 v8, v12, v8
	v_and_b32_e32 v9, 32, v9
	v_ashrrev_i16_sdwa v10, v146, sext(v10) dst_sel:DWORD dst_unused:UNUSED_PAD src0_sel:DWORD src1_sel:BYTE_0
	v_and_b32_e32 v14, -16, v14
	v_lshlrev_b32_e32 v15, 5, v15
	v_sub_u32_e32 v16, v16, v17
	v_lshlrev_b32_e32 v20, 3, v21
	v_ashrrev_i32_e32 v24, 6, v23
	v_and_b32_e32 v23, 0xc0, v23
	v_add_u32_sdwa v10, v9, sext(v10) dst_sel:DWORD dst_unused:UNUSED_PAD src0_sel:DWORD src1_sel:WORD_0
	v_ashrrev_i32_e32 v9, 31, v8
	v_add_u32_e32 v14, v18, v14
	v_and_b32_e32 v15, 32, v15
	v_ashrrev_i16_sdwa v16, v146, sext(v16) dst_sel:DWORD dst_unused:UNUSED_PAD src0_sel:DWORD src1_sel:BYTE_0
	v_and_b32_e32 v20, -16, v20
	v_lshlrev_b32_e32 v21, 5, v21
	v_sub_u32_e32 v22, v22, v23
	s_ashr_i32 s41, s40, 31
	v_lshlrev_b64 v[8:9], 11, v[8:9]
	v_ashrrev_i32_e32 v11, 31, v10
	v_add_u32_sdwa v16, v15, sext(v16) dst_sel:DWORD dst_unused:UNUSED_PAD src0_sel:DWORD src1_sel:WORD_0
	v_ashrrev_i32_e32 v15, 31, v14
	v_add_u32_e32 v20, v24, v20
	v_and_b32_e32 v21, 32, v21
	v_ashrrev_i16_sdwa v22, v146, sext(v22) dst_sel:DWORD dst_unused:UNUSED_PAD src0_sel:DWORD src1_sel:BYTE_0
	s_lshl_b64 s[6:7], s[40:41], 11
	v_lshl_add_u64 v[12:13], s[10:11], 0, v[8:9]
	v_lshlrev_b64 v[10:11], 1, v[10:11]
	v_lshlrev_b64 v[14:15], 11, v[14:15]
	v_ashrrev_i32_e32 v17, 31, v16
	v_add_u32_sdwa v22, v21, sext(v22) dst_sel:DWORD dst_unused:UNUSED_PAD src0_sel:DWORD src1_sel:WORD_0
	v_ashrrev_i32_e32 v21, 31, v20
	s_add_u32 s8, s14, s6
	v_lshl_add_u64 v[12:13], v[12:13], 0, v[10:11]
	v_lshl_add_u64 v[18:19], s[10:11], 0, v[14:15]
	v_lshlrev_b64 v[16:17], 1, v[16:17]
	v_lshlrev_b64 v[20:21], 11, v[20:21]
	v_ashrrev_i32_e32 v23, 31, v22
	v_add_u32_e32 v26, 0x6000, v78
	s_addc_u32 s9, s15, s7
	v_lshl_add_u64 v[18:19], v[18:19], 0, v[16:17]
	s_mov_b32 m0, s19
	v_lshl_add_u64 v[24:25], s[10:11], 0, v[20:21]
	v_lshlrev_b64 v[22:23], 1, v[22:23]
	v_readfirstlane_b32 s10, v26
	v_add_u32_e32 v28, 0x8000, v78
	v_lshl_add_u64 v[24:25], v[24:25], 0, v[22:23]
	s_mov_b32 m0, s10
	v_lshl_add_u64 v[26:27], s[8:9], 0, v[2:3]
	v_readfirstlane_b32 s10, v28
	v_add_u32_e32 v37, 0xa000, v78
	v_lshl_add_u64 v[26:27], v[26:27], 0, v[4:5]
	s_mov_b32 m0, s10
	v_lshl_add_u64 v[28:29], s[8:9], 0, v[8:9]
	v_readfirstlane_b32 s8, v37
	v_add_u32_e32 v37, 0xc000, v78
	v_lshl_add_u64 v[28:29], v[28:29], 0, v[10:11]
	s_mov_b32 m0, s8
	v_readfirstlane_b32 s8, v37
	v_lshl_add_u64 v[6:7], v[6:7], 0, s[30:31]
	s_mov_b32 m0, s8
	s_mov_b32 s3, 2
	v_lshl_add_u64 v[6:7], v[12:13], 0, s[30:31]
	v_add_u32_e32 v12, 0xe000, v78
	v_add3_u32 v80, v30, 0, v32
	v_readfirstlane_b32 s8, v12
	s_mov_b32 m0, s8
	s_add_i32 s8, 0, 0xc000
	v_add_u32_e32 v12, s8, v35
	v_readfirstlane_b32 s9, v12
	v_add_u32_e32 v12, s8, v36
	v_lshl_add_u64 v[6:7], v[18:19], 0, s[30:31]
	s_mov_b32 m0, s9
	v_readfirstlane_b32 s8, v12
	v_add_u32_e32 v12, s54, v33
	v_lshl_add_u64 v[6:7], v[24:25], 0, s[30:31]
	s_mov_b32 m0, s8
	v_readfirstlane_b32 s8, v12
	v_add_u32_e32 v12, s54, v34
	v_lshl_add_u64 v[6:7], v[26:27], 0, s[30:31]
	s_mov_b32 m0, s8
	v_readfirstlane_b32 s8, v12
	v_lshl_add_u64 v[6:7], v[28:29], 0, s[30:31]
	s_mov_b32 m0, s8
	s_add_i32 s8, 0, 0x8000
	v_lshl_add_u64 v[6:7], s[6:7], 0, v[8:9]
	v_lshl_add_u64 v[6:7], v[6:7], 0, v[10:11]
	v_lshl_add_u64 v[66:67], s[0:1], 0, v[6:7]
	v_lshl_add_u64 v[6:7], s[6:7], 0, v[2:3]
	v_lshl_add_u64 v[6:7], v[6:7], 0, v[4:5]
	v_lshl_add_u64 v[68:69], s[0:1], 0, v[6:7]
	v_lshl_add_u64 v[6:7], s[4:5], 0, v[20:21]
	v_lshl_add_u64 v[6:7], v[6:7], 0, v[22:23]
	v_lshl_add_u64 v[70:71], s[90:91], 0, v[6:7]
	v_lshl_add_u64 v[6:7], s[4:5], 0, v[14:15]
	v_lshl_add_u64 v[6:7], v[6:7], 0, v[16:17]
	v_lshl_add_u64 v[2:3], s[4:5], 0, v[2:3]
	v_lshl_add_u64 v[72:73], s[90:91], 0, v[6:7]
	v_lshl_add_u64 v[6:7], s[4:5], 0, v[8:9]
	v_lshl_add_u64 v[2:3], v[2:3], 0, v[4:5]
	v_lshl_add_u64 v[6:7], v[6:7], 0, v[10:11]
	v_lshl_add_u64 v[76:77], s[90:91], 0, v[2:3]
	v_mov_b32_e32 v2, 0
	v_add3_u32 v79, v31, s8, v32
	v_lshl_add_u64 v[74:75], s[90:91], 0, v[6:7]
	s_mov_b32 s6, 0
	s_mov_b64 s[4:5], 0
	v_mov_b32_e32 v3, v2
	v_mov_b32_e32 v4, v2
	v_mov_b32_e32 v5, v2
	v_mov_b32_e32 v6, v2
	v_mov_b32_e32 v7, v2
	v_mov_b32_e32 v8, v2
	v_mov_b32_e32 v9, v2
	v_mov_b32_e32 v10, v2
	v_mov_b32_e32 v11, v2
	v_mov_b32_e32 v12, v2
	v_mov_b32_e32 v13, v2
	v_mov_b32_e32 v14, v2
	v_mov_b32_e32 v15, v2
	v_mov_b32_e32 v16, v2
	v_mov_b32_e32 v17, v2
	v_mov_b32_e32 v18, v2
	v_mov_b32_e32 v19, v2
	v_mov_b32_e32 v20, v2
	v_mov_b32_e32 v21, v2
	v_mov_b32_e32 v22, v2
	v_mov_b32_e32 v23, v2
	v_mov_b32_e32 v24, v2
	v_mov_b32_e32 v25, v2
	v_mov_b32_e32 v26, v2
	v_mov_b32_e32 v27, v2
	v_mov_b32_e32 v28, v2
	v_mov_b32_e32 v29, v2
	v_mov_b32_e32 v30, v2
	v_mov_b32_e32 v31, v2
	v_mov_b32_e32 v32, v2
	v_mov_b32_e32 v33, v2
	v_mov_b32_e32 v34, v2
	v_mov_b32_e32 v35, v2
	v_mov_b32_e32 v36, v2
	v_mov_b32_e32 v37, v2
	v_mov_b32_e32 v38, v2
	v_mov_b32_e32 v39, v2
	v_mov_b32_e32 v40, v2
	v_mov_b32_e32 v41, v2
	v_mov_b32_e32 v42, v2
	v_mov_b32_e32 v43, v2
	v_mov_b32_e32 v44, v2
	v_mov_b32_e32 v45, v2
	v_mov_b32_e32 v46, v2
	v_mov_b32_e32 v47, v2
	v_mov_b32_e32 v48, v2
	v_mov_b32_e32 v49, v2
	v_mov_b32_e32 v50, v2
	v_mov_b32_e32 v51, v2
	v_mov_b32_e32 v52, v2
	v_mov_b32_e32 v53, v2
	v_mov_b32_e32 v54, v2
	v_mov_b32_e32 v55, v2
	v_mov_b32_e32 v56, v2
	v_mov_b32_e32 v57, v2
	v_mov_b32_e32 v58, v2
	v_mov_b32_e32 v59, v2
	v_mov_b32_e32 v60, v2
	v_mov_b32_e32 v61, v2
	v_mov_b32_e32 v62, v2
	v_mov_b32_e32 v63, v2
	v_mov_b32_e32 v64, v2
	v_mov_b32_e32 v65, v2
.LBB0_277:
	v_readlane_b32 s70, v243, 2
	s_cmp_lg_u32 s70, 0
	s_cbranch_scc1 .Lgx_have
	s_mov_b32 s68, s17
	s_mov_b32 s69, s18
	s_lshl_b32 s38, s68, 19
	s_add_u32 s4, s24, s38
	s_addc_u32 s5, s25, 0
	s_lshl_b32 s38, s69, 18
	s_add_u32 s42, s14, s38
	s_addc_u32 s43, s15, 0
	v_and_b32_e32 v226, 63, v142
	v_lshlrev_b32_e32 v222, 4, v226
	v_lshrrev_b32_e32 v227, 5, v226
	v_lshlrev_b32_e32 v227, 5, v227
	v_xor_b32_e32 v222, v222, v227
	v_lshrrev_b32_e32 v226, 6, v142
	v_and_b32_e32 v227, 1, v226
	v_lshrrev_b32_e32 v226, 1, v226
	v_lshrrev_b32_e32 v228, 6, v222
	v_lshl_add_u32 v226, v226, 4, v228
	v_mul_u32_u24_e32 v226, 0x800, v226
	v_and_b32_e32 v222, 63, v222
	v_lshl_add_u32 v222, v227, 6, v222
	v_add_u32_e32 v222, v222, v226
	v_add_u32_e32 v223, 0x20000, v222
	v_add_u32_e32 v224, 0x20000, v223
	v_add_u32_e32 v225, 0x20000, v224
	v_add_u32_e32 v218, 0x0, v78
	s_nop 0
	v_readfirstlane_b32 s7, v218
	s_add_u32 m0, s7, 0x0
	s_nop 0
	global_load_lds_dwordx4 v222, s[4:5]
	s_add_u32 m0, s7, 0x2000
	s_nop 0
	global_load_lds_dwordx4 v223, s[4:5]
	s_add_u32 m0, s7, 0x4000
	s_nop 0
	global_load_lds_dwordx4 v224, s[4:5]
	s_add_u32 m0, s7, 0x6000
	s_nop 0
	global_load_lds_dwordx4 v225, s[4:5]
	s_add_u32 m0, s7, 0x8000
	s_nop 0
	global_load_lds_dwordx4 v222, s[42:43]
	s_add_u32 m0, s7, 0xa000
	s_nop 0
	global_load_lds_dwordx4 v223, s[42:43]
	s_add_u32 s4, s4, 0x80
	s_addc_u32 s5, s5, 0
	s_add_u32 s42, s42, 0x80
	s_addc_u32 s43, s43, 0
	v_add_u32_e32 v218, 0xc000, v78
	s_nop 0
	v_readfirstlane_b32 s7, v218
	s_add_u32 m0, s7, 0x0
	s_nop 0
	global_load_lds_dwordx4 v222, s[4:5]
	s_add_u32 m0, s7, 0x2000
	s_nop 0
	global_load_lds_dwordx4 v223, s[4:5]
	s_add_u32 m0, s7, 0x4000
	s_nop 0
	global_load_lds_dwordx4 v224, s[4:5]
	s_add_u32 m0, s7, 0x6000
	s_nop 0
	global_load_lds_dwordx4 v225, s[4:5]
	s_add_u32 m0, s7, 0x8000
	s_nop 0
	global_load_lds_dwordx4 v222, s[42:43]
	s_add_u32 m0, s7, 0xa000
	s_nop 0
	global_load_lds_dwordx4 v223, s[42:43]
	s_add_u32 s4, s4, 0x80
	s_addc_u32 s5, s5, 0
	s_add_u32 s42, s42, 0x80
	s_addc_u32 s43, s43, 0
	s_mov_b32 s32, 14
	s_branch .Lgx_go
.Lgx_have:
	v_readlane_b32 s4, v243, 3
	v_readlane_b32 s5, v243, 4
	v_readlane_b32 s42, v243, 5
	v_readlane_b32 s43, v243, 6
	s_mov_b32 s32, 14
.Lgx_go:
.Lgb_gwin:
	s_waitcnt vmcnt(6)
	s_barrier
	s_mul_i32 s7, s6, 0xc000
	v_add_u32_e32 v220, s7, v80
	v_add_u32_e32 v221, s7, v79
	ds_read_b128 v[82:85], v220 offset:0
	ds_read_b128 v[86:89], v220 offset:2048
	ds_read_b128 v[90:93], v220 offset:4096
	ds_read_b128 v[94:97], v220 offset:6144
	ds_read_b128 v[98:101], v221 offset:0
	ds_read_b128 v[102:105], v221 offset:2048
	ds_read_b128 v[106:109], v221 offset:4096
	ds_read_b128 v[110:113], v221 offset:6144
	s_mul_i32 s7, s3, 0xc000
	v_add_u32_e32 v218, s7, v78
	s_nop 0
	v_readfirstlane_b32 s7, v218
	s_add_u32 m0, s7, 0x0
	s_nop 0
	global_load_lds_dwordx4 v222, s[4:5]
	s_add_u32 m0, s7, 0x2000
	s_nop 0
	global_load_lds_dwordx4 v223, s[4:5]
	s_add_u32 m0, s7, 0x4000
	s_nop 0
	global_load_lds_dwordx4 v224, s[4:5]
	s_add_u32 m0, s7, 0x6000
	s_nop 0
	global_load_lds_dwordx4 v225, s[4:5]
	s_add_u32 m0, s7, 0x8000
	s_nop 0
	global_load_lds_dwordx4 v222, s[42:43]
	s_add_u32 m0, s7, 0xa000
	s_nop 0
	global_load_lds_dwordx4 v223, s[42:43]
	ds_read_b128 v[114:117], v220 offset:1024
	ds_read_b128 v[118:121], v220 offset:3072
	ds_read_b128 v[122:125], v220 offset:5120
	ds_read_b128 v[126:129], v220 offset:7168
	ds_read_b128 v[134:137], v221 offset:1024
	ds_read_b128 v[138:141], v221 offset:3072
	ds_read_b128 v[162:165], v221 offset:5120
	ds_read_b128 v[166:169], v221 offset:7168
	s_waitcnt lgkmcnt(8)
	v_mfma_f32_16x16x32_bf16 v[62:65], v[98:101], v[82:85], v[62:65]
	v_mfma_f32_16x16x32_bf16 v[58:61], v[102:105], v[82:85], v[58:61]
	v_mfma_f32_16x16x32_bf16 v[54:57], v[106:109], v[82:85], v[54:57]
	v_mfma_f32_16x16x32_bf16 v[50:53], v[110:113], v[82:85], v[50:53]
	v_mfma_f32_16x16x32_bf16 v[46:49], v[98:101], v[86:89], v[46:49]
	v_mfma_f32_16x16x32_bf16 v[42:45], v[102:105], v[86:89], v[42:45]
	v_mfma_f32_16x16x32_bf16 v[38:41], v[106:109], v[86:89], v[38:41]
	v_mfma_f32_16x16x32_bf16 v[34:37], v[110:113], v[86:89], v[34:37]
	v_mfma_f32_16x16x32_bf16 v[30:33], v[98:101], v[90:93], v[30:33]
	v_mfma_f32_16x16x32_bf16 v[26:29], v[102:105], v[90:93], v[26:29]
	v_mfma_f32_16x16x32_bf16 v[22:25], v[106:109], v[90:93], v[22:25]
	v_mfma_f32_16x16x32_bf16 v[18:21], v[110:113], v[90:93], v[18:21]
	v_mfma_f32_16x16x32_bf16 v[14:17], v[98:101], v[94:97], v[14:17]
	v_mfma_f32_16x16x32_bf16 v[10:13], v[102:105], v[94:97], v[10:13]
	v_mfma_f32_16x16x32_bf16 v[6:9], v[106:109], v[94:97], v[6:9]
	v_mfma_f32_16x16x32_bf16 v[2:5], v[110:113], v[94:97], v[2:5]
	s_waitcnt lgkmcnt(0)
	s_add_i32 s7, s6, 1
	s_cmp_lg_u32 s6, 2
	s_cselect_b32 s6, s7, 0
	s_add_i32 s7, s3, 1
	s_cmp_lg_u32 s3, 2
	s_cselect_b32 s3, s7, 0
	s_add_u32 s4, s4, 0x80
	s_addc_u32 s5, s5, 0
	s_add_u32 s42, s42, 0x80
	s_addc_u32 s43, s43, 0
	s_sub_u32 s32, s32, 1
.Lgbl_gwin:
	s_waitcnt vmcnt(6)
	s_barrier
	s_mul_i32 s7, s6, 0xc000
	v_add_u32_e32 v220, s7, v80
	v_add_u32_e32 v221, s7, v79
	ds_read_b128 v[82:85], v220 offset:0
	ds_read_b128 v[86:89], v220 offset:2048
	ds_read_b128 v[90:93], v220 offset:4096
	ds_read_b128 v[94:97], v220 offset:6144
	ds_read_b128 v[98:101], v221 offset:0
	ds_read_b128 v[102:105], v221 offset:2048
	ds_read_b128 v[106:109], v221 offset:4096
	ds_read_b128 v[110:113], v221 offset:6144
	s_mul_i32 s7, s3, 0xc000
	v_add_u32_e32 v218, s7, v78
	s_nop 0
	v_readfirstlane_b32 s7, v218
	v_mfma_f32_16x16x32_bf16 v[62:65], v[134:137], v[114:117], v[62:65]
	v_mfma_f32_16x16x32_bf16 v[58:61], v[138:141], v[114:117], v[58:61]
	s_add_u32 m0, s7, 0x0
	s_nop 0
	global_load_lds_dwordx4 v222, s[4:5]
	v_mfma_f32_16x16x32_bf16 v[54:57], v[162:165], v[114:117], v[54:57]
	v_mfma_f32_16x16x32_bf16 v[50:53], v[166:169], v[114:117], v[50:53]
	s_add_u32 m0, s7, 0x2000
	s_nop 0
	global_load_lds_dwordx4 v223, s[4:5]
	v_mfma_f32_16x16x32_bf16 v[46:49], v[134:137], v[118:121], v[46:49]
	v_mfma_f32_16x16x32_bf16 v[42:45], v[138:141], v[118:121], v[42:45]
	s_add_u32 m0, s7, 0x4000
	s_nop 0
	global_load_lds_dwordx4 v224, s[4:5]
	v_mfma_f32_16x16x32_bf16 v[38:41], v[162:165], v[118:121], v[38:41]
	v_mfma_f32_16x16x32_bf16 v[34:37], v[166:169], v[118:121], v[34:37]
	s_add_u32 m0, s7, 0x6000
	s_nop 0
	global_load_lds_dwordx4 v225, s[4:5]
	v_mfma_f32_16x16x32_bf16 v[30:33], v[134:137], v[122:125], v[30:33]
	v_mfma_f32_16x16x32_bf16 v[26:29], v[138:141], v[122:125], v[26:29]
	s_add_u32 m0, s7, 0x8000
	s_nop 0
	global_load_lds_dwordx4 v222, s[42:43]
	v_mfma_f32_16x16x32_bf16 v[22:25], v[162:165], v[122:125], v[22:25]
	v_mfma_f32_16x16x32_bf16 v[18:21], v[166:169], v[122:125], v[18:21]
	s_add_u32 m0, s7, 0xa000
	s_nop 0
	global_load_lds_dwordx4 v223, s[42:43]
	v_mfma_f32_16x16x32_bf16 v[14:17], v[134:137], v[126:129], v[14:17]
	v_mfma_f32_16x16x32_bf16 v[10:13], v[138:141], v[126:129], v[10:13]
	v_mfma_f32_16x16x32_bf16 v[6:9], v[162:165], v[126:129], v[6:9]
	v_mfma_f32_16x16x32_bf16 v[2:5], v[166:169], v[126:129], v[2:5]
	ds_read_b128 v[114:117], v220 offset:1024
	ds_read_b128 v[118:121], v220 offset:3072
	ds_read_b128 v[122:125], v220 offset:5120
	ds_read_b128 v[126:129], v220 offset:7168
	ds_read_b128 v[134:137], v221 offset:1024
	ds_read_b128 v[138:141], v221 offset:3072
	ds_read_b128 v[162:165], v221 offset:5120
	ds_read_b128 v[166:169], v221 offset:7168
	s_waitcnt lgkmcnt(8)
	v_mfma_f32_16x16x32_bf16 v[62:65], v[98:101], v[82:85], v[62:65]
	v_mfma_f32_16x16x32_bf16 v[58:61], v[102:105], v[82:85], v[58:61]
	v_mfma_f32_16x16x32_bf16 v[54:57], v[106:109], v[82:85], v[54:57]
	v_mfma_f32_16x16x32_bf16 v[50:53], v[110:113], v[82:85], v[50:53]
	v_mfma_f32_16x16x32_bf16 v[46:49], v[98:101], v[86:89], v[46:49]
	v_mfma_f32_16x16x32_bf16 v[42:45], v[102:105], v[86:89], v[42:45]
	v_mfma_f32_16x16x32_bf16 v[38:41], v[106:109], v[86:89], v[38:41]
	v_mfma_f32_16x16x32_bf16 v[34:37], v[110:113], v[86:89], v[34:37]
	v_mfma_f32_16x16x32_bf16 v[30:33], v[98:101], v[90:93], v[30:33]
	v_mfma_f32_16x16x32_bf16 v[26:29], v[102:105], v[90:93], v[26:29]
	v_mfma_f32_16x16x32_bf16 v[22:25], v[106:109], v[90:93], v[22:25]
	v_mfma_f32_16x16x32_bf16 v[18:21], v[110:113], v[90:93], v[18:21]
	v_mfma_f32_16x16x32_bf16 v[14:17], v[98:101], v[94:97], v[14:17]
	v_mfma_f32_16x16x32_bf16 v[10:13], v[102:105], v[94:97], v[10:13]
	v_mfma_f32_16x16x32_bf16 v[6:9], v[106:109], v[94:97], v[6:9]
	v_mfma_f32_16x16x32_bf16 v[2:5], v[110:113], v[94:97], v[2:5]
	s_waitcnt lgkmcnt(0)
	s_add_i32 s7, s6, 1
	s_cmp_lg_u32 s6, 2
	s_cselect_b32 s6, s7, 0
	s_add_i32 s7, s3, 1
	s_cmp_lg_u32 s3, 2
	s_cselect_b32 s3, s7, 0
	s_add_u32 s4, s4, 0x80
	s_addc_u32 s5, s5, 0
	s_add_u32 s42, s42, 0x80
	s_addc_u32 s43, s43, 0
	s_sub_u32 s32, s32, 1
	s_cmp_lg_u32 s32, 0
	s_cbranch_scc1 .Lgbl_gwin
	s_waitcnt vmcnt(6)
	s_barrier
	s_mul_i32 s7, s6, 0xc000
	v_add_u32_e32 v220, s7, v80
	v_add_u32_e32 v221, s7, v79
	ds_read_b128 v[82:85], v220 offset:0
	ds_read_b128 v[86:89], v220 offset:2048
	ds_read_b128 v[90:93], v220 offset:4096
	ds_read_b128 v[94:97], v220 offset:6144
	ds_read_b128 v[98:101], v221 offset:0
	ds_read_b128 v[102:105], v221 offset:2048
	ds_read_b128 v[106:109], v221 offset:4096
	ds_read_b128 v[110:113], v221 offset:6144
	v_mfma_f32_16x16x32_bf16 v[62:65], v[134:137], v[114:117], v[62:65]
	v_mfma_f32_16x16x32_bf16 v[58:61], v[138:141], v[114:117], v[58:61]
	v_mfma_f32_16x16x32_bf16 v[54:57], v[162:165], v[114:117], v[54:57]
	v_mfma_f32_16x16x32_bf16 v[50:53], v[166:169], v[114:117], v[50:53]
	v_mfma_f32_16x16x32_bf16 v[46:49], v[134:137], v[118:121], v[46:49]
	v_mfma_f32_16x16x32_bf16 v[42:45], v[138:141], v[118:121], v[42:45]
	v_mfma_f32_16x16x32_bf16 v[38:41], v[162:165], v[118:121], v[38:41]
	v_mfma_f32_16x16x32_bf16 v[34:37], v[166:169], v[118:121], v[34:37]
	v_mfma_f32_16x16x32_bf16 v[30:33], v[134:137], v[122:125], v[30:33]
	v_mfma_f32_16x16x32_bf16 v[26:29], v[138:141], v[122:125], v[26:29]
	v_mfma_f32_16x16x32_bf16 v[22:25], v[162:165], v[122:125], v[22:25]
	v_mfma_f32_16x16x32_bf16 v[18:21], v[166:169], v[122:125], v[18:21]
	v_mfma_f32_16x16x32_bf16 v[14:17], v[134:137], v[126:129], v[14:17]
	v_mfma_f32_16x16x32_bf16 v[10:13], v[138:141], v[126:129], v[10:13]
	v_mfma_f32_16x16x32_bf16 v[6:9], v[162:165], v[126:129], v[6:9]
	v_mfma_f32_16x16x32_bf16 v[2:5], v[166:169], v[126:129], v[2:5]
	ds_read_b128 v[114:117], v220 offset:1024
	ds_read_b128 v[118:121], v220 offset:3072
	ds_read_b128 v[122:125], v220 offset:5120
	ds_read_b128 v[126:129], v220 offset:7168
	ds_read_b128 v[134:137], v221 offset:1024
	ds_read_b128 v[138:141], v221 offset:3072
	ds_read_b128 v[162:165], v221 offset:5120
	ds_read_b128 v[166:169], v221 offset:7168
	s_waitcnt lgkmcnt(8)
	v_mfma_f32_16x16x32_bf16 v[62:65], v[98:101], v[82:85], v[62:65]
	v_mfma_f32_16x16x32_bf16 v[58:61], v[102:105], v[82:85], v[58:61]
	v_mfma_f32_16x16x32_bf16 v[54:57], v[106:109], v[82:85], v[54:57]
	v_mfma_f32_16x16x32_bf16 v[50:53], v[110:113], v[82:85], v[50:53]
	v_mfma_f32_16x16x32_bf16 v[46:49], v[98:101], v[86:89], v[46:49]
	v_mfma_f32_16x16x32_bf16 v[42:45], v[102:105], v[86:89], v[42:45]
	v_mfma_f32_16x16x32_bf16 v[38:41], v[106:109], v[86:89], v[38:41]
	v_mfma_f32_16x16x32_bf16 v[34:37], v[110:113], v[86:89], v[34:37]
	v_mfma_f32_16x16x32_bf16 v[30:33], v[98:101], v[90:93], v[30:33]
	v_mfma_f32_16x16x32_bf16 v[26:29], v[102:105], v[90:93], v[26:29]
	v_mfma_f32_16x16x32_bf16 v[22:25], v[106:109], v[90:93], v[22:25]
	v_mfma_f32_16x16x32_bf16 v[18:21], v[110:113], v[90:93], v[18:21]
	v_mfma_f32_16x16x32_bf16 v[14:17], v[98:101], v[94:97], v[14:17]
	v_mfma_f32_16x16x32_bf16 v[10:13], v[102:105], v[94:97], v[10:13]
	v_mfma_f32_16x16x32_bf16 v[6:9], v[106:109], v[94:97], v[6:9]
	v_mfma_f32_16x16x32_bf16 v[2:5], v[110:113], v[94:97], v[2:5]
	s_waitcnt lgkmcnt(0)
	s_add_i32 s7, s6, 1
	s_cmp_lg_u32 s6, 2
	s_cselect_b32 s6, s7, 0
	s_add_i32 s7, s3, 1
	s_cmp_lg_u32 s3, 2
	s_cselect_b32 s3, s7, 0
	s_waitcnt vmcnt(0)
	s_barrier
	s_mul_i32 s7, s6, 0xc000
	v_add_u32_e32 v220, s7, v80
	v_add_u32_e32 v221, s7, v79
	ds_read_b128 v[82:85], v220 offset:0
	ds_read_b128 v[86:89], v220 offset:2048
	ds_read_b128 v[90:93], v220 offset:4096
	ds_read_b128 v[94:97], v220 offset:6144
	ds_read_b128 v[98:101], v221 offset:0
	ds_read_b128 v[102:105], v221 offset:2048
	ds_read_b128 v[106:109], v221 offset:4096
	ds_read_b128 v[110:113], v221 offset:6144
	v_mfma_f32_16x16x32_bf16 v[62:65], v[134:137], v[114:117], v[62:65]
	v_mfma_f32_16x16x32_bf16 v[58:61], v[138:141], v[114:117], v[58:61]
	v_mfma_f32_16x16x32_bf16 v[54:57], v[162:165], v[114:117], v[54:57]
	v_mfma_f32_16x16x32_bf16 v[50:53], v[166:169], v[114:117], v[50:53]
	v_mfma_f32_16x16x32_bf16 v[46:49], v[134:137], v[118:121], v[46:49]
	v_mfma_f32_16x16x32_bf16 v[42:45], v[138:141], v[118:121], v[42:45]
	v_mfma_f32_16x16x32_bf16 v[38:41], v[162:165], v[118:121], v[38:41]
	v_mfma_f32_16x16x32_bf16 v[34:37], v[166:169], v[118:121], v[34:37]
	v_mfma_f32_16x16x32_bf16 v[30:33], v[134:137], v[122:125], v[30:33]
	v_mfma_f32_16x16x32_bf16 v[26:29], v[138:141], v[122:125], v[26:29]
	v_mfma_f32_16x16x32_bf16 v[22:25], v[162:165], v[122:125], v[22:25]
	v_mfma_f32_16x16x32_bf16 v[18:21], v[166:169], v[122:125], v[18:21]
	v_mfma_f32_16x16x32_bf16 v[14:17], v[134:137], v[126:129], v[14:17]
	v_mfma_f32_16x16x32_bf16 v[10:13], v[138:141], v[126:129], v[10:13]
	v_mfma_f32_16x16x32_bf16 v[6:9], v[162:165], v[126:129], v[6:9]
	v_mfma_f32_16x16x32_bf16 v[2:5], v[166:169], v[126:129], v[2:5]
	ds_read_b128 v[114:117], v220 offset:1024
	ds_read_b128 v[118:121], v220 offset:3072
	ds_read_b128 v[122:125], v220 offset:5120
	ds_read_b128 v[126:129], v220 offset:7168
	ds_read_b128 v[134:137], v221 offset:1024
	ds_read_b128 v[138:141], v221 offset:3072
	ds_read_b128 v[162:165], v221 offset:5120
	ds_read_b128 v[166:169], v221 offset:7168
	s_waitcnt lgkmcnt(8)
	v_mfma_f32_16x16x32_bf16 v[62:65], v[98:101], v[82:85], v[62:65]
	v_mfma_f32_16x16x32_bf16 v[58:61], v[102:105], v[82:85], v[58:61]
	v_mfma_f32_16x16x32_bf16 v[54:57], v[106:109], v[82:85], v[54:57]
	v_mfma_f32_16x16x32_bf16 v[50:53], v[110:113], v[82:85], v[50:53]
	v_mfma_f32_16x16x32_bf16 v[46:49], v[98:101], v[86:89], v[46:49]
	v_mfma_f32_16x16x32_bf16 v[42:45], v[102:105], v[86:89], v[42:45]
	v_mfma_f32_16x16x32_bf16 v[38:41], v[106:109], v[86:89], v[38:41]
	v_mfma_f32_16x16x32_bf16 v[34:37], v[110:113], v[86:89], v[34:37]
	v_mfma_f32_16x16x32_bf16 v[30:33], v[98:101], v[90:93], v[30:33]
	v_mfma_f32_16x16x32_bf16 v[26:29], v[102:105], v[90:93], v[26:29]
	v_mfma_f32_16x16x32_bf16 v[22:25], v[106:109], v[90:93], v[22:25]
	v_mfma_f32_16x16x32_bf16 v[18:21], v[110:113], v[90:93], v[18:21]
	v_mfma_f32_16x16x32_bf16 v[14:17], v[98:101], v[94:97], v[14:17]
	v_mfma_f32_16x16x32_bf16 v[10:13], v[102:105], v[94:97], v[10:13]
	v_mfma_f32_16x16x32_bf16 v[6:9], v[106:109], v[94:97], v[6:9]
	v_mfma_f32_16x16x32_bf16 v[2:5], v[110:113], v[94:97], v[2:5]
	s_waitcnt lgkmcnt(0)
	s_add_i32 s7, s6, 1
	s_cmp_lg_u32 s6, 2
	s_cselect_b32 s6, s7, 0
	s_add_i32 s7, s3, 1
	s_cmp_lg_u32 s3, 2
	s_cselect_b32 s3, s7, 0
	v_mfma_f32_16x16x32_bf16 v[62:65], v[134:137], v[114:117], v[62:65]
	v_mfma_f32_16x16x32_bf16 v[58:61], v[138:141], v[114:117], v[58:61]
	v_mfma_f32_16x16x32_bf16 v[54:57], v[162:165], v[114:117], v[54:57]
	v_mfma_f32_16x16x32_bf16 v[50:53], v[166:169], v[114:117], v[50:53]
	v_mfma_f32_16x16x32_bf16 v[46:49], v[134:137], v[118:121], v[46:49]
	v_mfma_f32_16x16x32_bf16 v[42:45], v[138:141], v[118:121], v[42:45]
	v_mfma_f32_16x16x32_bf16 v[38:41], v[162:165], v[118:121], v[38:41]
	v_mfma_f32_16x16x32_bf16 v[34:37], v[166:169], v[118:121], v[34:37]
	v_mfma_f32_16x16x32_bf16 v[30:33], v[134:137], v[122:125], v[30:33]
	v_mfma_f32_16x16x32_bf16 v[26:29], v[138:141], v[122:125], v[26:29]
	v_mfma_f32_16x16x32_bf16 v[22:25], v[162:165], v[122:125], v[22:25]
	v_mfma_f32_16x16x32_bf16 v[18:21], v[166:169], v[122:125], v[18:21]
	v_mfma_f32_16x16x32_bf16 v[14:17], v[134:137], v[126:129], v[14:17]
	v_mfma_f32_16x16x32_bf16 v[10:13], v[138:141], v[126:129], v[10:13]
	v_mfma_f32_16x16x32_bf16 v[6:9], v[162:165], v[126:129], v[6:9]
	v_mfma_f32_16x16x32_bf16 v[2:5], v[166:169], v[126:129], v[2:5]
.Lgd_gwin:
	s_nop 7
	s_nop 1
	v_bfe_u32 v161, v0, 6, 1
	v_and_b32_e32 v134, 15, v0
	v_bfe_u32 v162, v0, 4, 2
	v_readlane_b32 s68, v215, 34
	v_readlane_b32 s69, v215, 48
	s_add_i32 s68, s16, s68
	s_cmp_ge_i32 s68, s69
	s_cbranch_scc1 .Lgx_nonext
	s_mul_i32 s70, s68, 9363
	s_lshr_b32 s70, s70, 16
	s_mul_i32 s69, s70, 7
	s_sub_u32 s69, s68, s69
	s_mov_b32 s68, s70
	v_readlane_b32 s38, v217, 0
	s_and_b32 s38, s38, 7
	s_lshl_b32 s4, s69, 3
	s_add_u32 s4, s4, s38
	s_add_u32 s4, s4, 16
	s_lshl_b32 s5, s38, 1
	s_add_u32 s5, s5, s69
	s_sub_u32 s70, s5, 3
	s_add_u32 s5, s5, 35
	s_cmp_lt_u32 s69, 5
	s_cselect_b32 s70, s70, s5
	s_cmp_lt_u32 s69, 3
	s_cselect_b32 s70, s4, s70
	s_mov_b32 s69, s70
	s_barrier
	s_lshl_b32 s38, s68, 19
	s_add_u32 s4, s24, s38
	s_addc_u32 s5, s25, 0
	s_lshl_b32 s38, s69, 18
	s_add_u32 s42, s14, s38
	s_addc_u32 s43, s15, 0
	v_and_b32_e32 v226, 63, v142
	v_lshlrev_b32_e32 v222, 4, v226
	v_lshrrev_b32_e32 v227, 5, v226
	v_lshlrev_b32_e32 v227, 5, v227
	v_xor_b32_e32 v222, v222, v227
	v_lshrrev_b32_e32 v226, 6, v142
	v_and_b32_e32 v227, 1, v226
	v_lshrrev_b32_e32 v226, 1, v226
	v_lshrrev_b32_e32 v228, 6, v222
	v_lshl_add_u32 v226, v226, 4, v228
	v_mul_u32_u24_e32 v226, 0x800, v226
	v_and_b32_e32 v222, 63, v222
	v_lshl_add_u32 v222, v227, 6, v222
	v_add_u32_e32 v222, v222, v226
	v_add_u32_e32 v223, 0x20000, v222
	v_add_u32_e32 v224, 0x20000, v223
	v_add_u32_e32 v225, 0x20000, v224
	v_add_u32_e32 v218, 0x0, v78
	s_nop 0
	v_readfirstlane_b32 s7, v218
	s_add_u32 m0, s7, 0x0
	s_nop 0
	global_load_lds_dwordx4 v222, s[4:5]
	s_add_u32 m0, s7, 0x2000
	s_nop 0
	global_load_lds_dwordx4 v223, s[4:5]
	s_add_u32 m0, s7, 0x4000
	s_nop 0
	global_load_lds_dwordx4 v224, s[4:5]
	s_add_u32 m0, s7, 0x6000
	s_nop 0
	global_load_lds_dwordx4 v225, s[4:5]
	s_add_u32 m0, s7, 0x8000
	s_nop 0
	global_load_lds_dwordx4 v222, s[42:43]
	s_add_u32 m0, s7, 0xa000
	s_nop 0
	global_load_lds_dwordx4 v223, s[42:43]
	s_add_u32 s4, s4, 0x80
	s_addc_u32 s5, s5, 0
	s_add_u32 s42, s42, 0x80
	s_addc_u32 s43, s43, 0
	v_add_u32_e32 v218, 0xc000, v78
	s_nop 0
	v_readfirstlane_b32 s7, v218
	s_add_u32 m0, s7, 0x0
	s_nop 0
	global_load_lds_dwordx4 v222, s[4:5]
	s_add_u32 m0, s7, 0x2000
	s_nop 0
	global_load_lds_dwordx4 v223, s[4:5]
	s_add_u32 m0, s7, 0x4000
	s_nop 0
	global_load_lds_dwordx4 v224, s[4:5]
	s_add_u32 m0, s7, 0x6000
	s_nop 0
	global_load_lds_dwordx4 v225, s[4:5]
	s_add_u32 m0, s7, 0x8000
	s_nop 0
	global_load_lds_dwordx4 v222, s[42:43]
	s_add_u32 m0, s7, 0xa000
	s_nop 0
	global_load_lds_dwordx4 v223, s[42:43]
	s_add_u32 s4, s4, 0x80
	s_addc_u32 s5, s5, 0
	s_add_u32 s42, s42, 0x80
	s_addc_u32 s43, s43, 0
	s_mov_b32 s32, 14
	v_writelane_b32 v243, s4, 3
	v_writelane_b32 v243, s5, 4
	v_writelane_b32 v243, s42, 5
	v_writelane_b32 v243, s43, 6
	s_mov_b32 s70, 1
	v_writelane_b32 v243, s70, 2
	s_branch .Lgx_done
.Lgx_nonext:
	s_mov_b32 s70, 0
	v_writelane_b32 v243, s70, 2
.Lgx_done:
	v_ashrrev_i32_e32 v0, 1, v0
	v_and_b32_e32 v163, 0xffffffc0, v0
	s_cmp_gt_i32 s18, 7
	s_mov_b64 s[4:5], -1
	s_cbranch_scc0 .LBB0_316
	s_cmp_gt_u32 s18, 15
	s_cbranch_scc0 .LBB0_305
	s_cmpk_gt_i32 s16, 0x6f
	s_cselect_b64 s[4:5], -1, 0
	s_add_i32 s3, s2, 0xfffff000
	s_lshr_b32 s3, s3, 10
	s_cmpk_lt_i32 s16, 0x70
	s_cselect_b64 s[6:7], -1, 0
	s_and_b64 s[8:9], s[6:7], exec
	s_movk_i32 s8, 0x70
	s_cselect_b32 s8, s8, 0x300
	s_and_b32 s8, s8, s2
	v_add_u32_e32 v136, s8, v163
	s_cmp_gt_u32 s18, 31
	s_mov_b64 s[8:9], -1
	s_cbranch_scc0 .LBB0_290
	s_cmp_gt_u32 s18, 39
	s_cbranch_scc0 .LBB0_283
	v_or_b32_e32 v0, s2, v134
	v_add_u32_e32 v66, v0, v163
	v_ashrrev_i32_e32 v67, 31, v66
	v_lshlrev_b64 v[68:69], 12, v[66:67]
	v_mul_f32_e32 v67, 0xbfb8aa3b, v62
	v_mul_f32_e32 v74, 0xbfb8aa3b, v63
	v_mul_f32_e32 v75, 0xbfb8aa3b, v64
	v_mul_f32_e32 v76, 0xbfb8aa3b, v65
	v_exp_f32_e32 v67, v67
	v_exp_f32_e32 v74, v74
	v_exp_f32_e32 v75, v75
	v_exp_f32_e32 v76, v76
	s_lshl_b64 s[8:9], s[40:41], 1
	s_add_u32 s8, s48, s8
	s_addc_u32 s9, s49, s9
	v_add_f32_e32 v67, 1.0, v67
	v_add_f32_e32 v74, 1.0, v74
	v_add_f32_e32 v75, 1.0, v75
	v_add_f32_e32 v76, 1.0, v76
	v_lshl_add_u64 v[68:69], s[8:9], 0, v[68:69]
	v_lshlrev_b32_e32 v0, 7, v161
	v_rcp_f32_e32 v67, v67
	v_rcp_f32_e32 v74, v74
	v_rcp_f32_e32 v75, v75
	v_rcp_f32_e32 v76, v76
	v_lshl_add_u64 v[70:71], v[68:69], 0, v[0:1]
	v_lshlrev_b32_e32 v68, 3, v162
	v_mov_b32_e32 v69, v1
	v_lshl_add_u64 v[72:73], v[70:71], 0, v[68:69]
	s_mov_b64 s[38:39], 0xa15d800
	s_mov_b32 s10, 0xa15d000
	v_lshl_add_u64 v[70:71], v[72:73], 0, s[38:39]
	v_add_co_u32_e32 v72, vcc, s10, v72
	v_cvt_pk_bf16_f32 v74, v67, v74
	v_cvt_pk_bf16_f32 v75, v75, v76
	v_addc_co_u32_e32 v73, vcc, 0, v73, vcc
	global_store_dwordx2 v[72:73], v[74:75], off offset:2048
	v_mul_f32_e32 v67, 0xbfb8aa3b, v58
	v_mul_f32_e32 v72, 0xbfb8aa3b, v59
	v_mul_f32_e32 v73, 0xbfb8aa3b, v60
	v_mul_f32_e32 v74, 0xbfb8aa3b, v61
	v_exp_f32_e32 v67, v67
	v_exp_f32_e32 v72, v72
	v_exp_f32_e32 v73, v73
	v_exp_f32_e32 v74, v74
	v_add_f32_e32 v67, 1.0, v67
	v_add_f32_e32 v72, 1.0, v72
	v_add_f32_e32 v73, 1.0, v73
	v_add_f32_e32 v74, 1.0, v74
	v_rcp_f32_e32 v67, v67
	v_rcp_f32_e32 v72, v72
	v_rcp_f32_e32 v73, v73
	v_rcp_f32_e32 v74, v74
	v_mul_f32_e32 v75, 0xbfb8aa3b, v48
	v_cvt_pk_bf16_f32 v72, v67, v72
	v_mul_f32_e32 v67, 0xbfb8aa3b, v54
	v_cvt_pk_bf16_f32 v73, v73, v74
	global_store_dwordx2 v[70:71], v[72:73], off offset:32
	v_mul_f32_e32 v72, 0xbfb8aa3b, v55
	v_mul_f32_e32 v73, 0xbfb8aa3b, v56
	v_mul_f32_e32 v74, 0xbfb8aa3b, v57
	v_exp_f32_e32 v67, v67
	v_exp_f32_e32 v72, v72
	v_exp_f32_e32 v73, v73
	v_exp_f32_e32 v74, v74
	v_add_f32_e32 v67, 1.0, v67
	v_add_f32_e32 v72, 1.0, v72
	v_add_f32_e32 v73, 1.0, v73
	v_add_f32_e32 v74, 1.0, v74
	v_rcp_f32_e32 v67, v67
	v_rcp_f32_e32 v72, v72
	v_rcp_f32_e32 v73, v73
	v_rcp_f32_e32 v74, v74
	v_mul_f32_e32 v76, 0xbfb8aa3b, v49
	v_cvt_pk_bf16_f32 v72, v67, v72
	v_mul_f32_e32 v67, 0xbfb8aa3b, v50
	v_cvt_pk_bf16_f32 v73, v73, v74
	global_store_dwordx2 v[70:71], v[72:73], off offset:64
	v_mul_f32_e32 v72, 0xbfb8aa3b, v51
	v_mul_f32_e32 v73, 0xbfb8aa3b, v52
	v_mul_f32_e32 v74, 0xbfb8aa3b, v53
	v_exp_f32_e32 v67, v67
	v_exp_f32_e32 v72, v72
	v_exp_f32_e32 v73, v73
	v_exp_f32_e32 v74, v74
	v_add_f32_e32 v67, 1.0, v67
	v_add_f32_e32 v72, 1.0, v72
	v_add_f32_e32 v73, 1.0, v73
	v_add_f32_e32 v74, 1.0, v74
	v_rcp_f32_e32 v67, v67
	v_rcp_f32_e32 v72, v72
	v_rcp_f32_e32 v73, v73
	v_rcp_f32_e32 v74, v74
	v_exp_f32_e32 v75, v75
	v_cvt_pk_bf16_f32 v72, v67, v72
	v_mul_f32_e32 v67, 0xbfb8aa3b, v46
	v_cvt_pk_bf16_f32 v73, v73, v74
	v_mul_f32_e32 v74, 0xbfb8aa3b, v47
	v_exp_f32_e32 v67, v67
	v_exp_f32_e32 v74, v74
	v_exp_f32_e32 v76, v76
	global_store_dwordx2 v[70:71], v[72:73], off offset:96
	v_or_b32_e32 v70, 16, v66
	v_ashrrev_i32_e32 v71, 31, v70
	v_lshlrev_b64 v[70:71], 12, v[70:71]
	v_add_f32_e32 v67, 1.0, v67
	v_add_f32_e32 v74, 1.0, v74
	v_add_f32_e32 v75, 1.0, v75
	v_add_f32_e32 v76, 1.0, v76
	v_lshl_add_u64 v[70:71], s[8:9], 0, v[70:71]
	v_rcp_f32_e32 v67, v67
	v_rcp_f32_e32 v74, v74
	v_rcp_f32_e32 v75, v75
	v_rcp_f32_e32 v76, v76
	v_lshl_add_u64 v[70:71], v[70:71], 0, v[0:1]
	v_lshl_add_u64 v[72:73], v[70:71], 0, v[68:69]
	v_lshl_add_u64 v[70:71], v[72:73], 0, s[38:39]
	v_add_co_u32_e32 v72, vcc, s10, v72
	v_cvt_pk_bf16_f32 v74, v67, v74
	v_cvt_pk_bf16_f32 v75, v75, v76
	v_addc_co_u32_e32 v73, vcc, 0, v73, vcc
	global_store_dwordx2 v[72:73], v[74:75], off offset:2048
	v_mul_f32_e32 v67, 0xbfb8aa3b, v42
	v_mul_f32_e32 v72, 0xbfb8aa3b, v43
	v_mul_f32_e32 v73, 0xbfb8aa3b, v44
	v_mul_f32_e32 v74, 0xbfb8aa3b, v45
	v_exp_f32_e32 v67, v67
	v_exp_f32_e32 v72, v72
	v_exp_f32_e32 v73, v73
	v_exp_f32_e32 v74, v74
	v_add_f32_e32 v67, 1.0, v67
	v_add_f32_e32 v72, 1.0, v72
	v_add_f32_e32 v73, 1.0, v73
	v_add_f32_e32 v74, 1.0, v74
	v_rcp_f32_e32 v67, v67
	v_rcp_f32_e32 v72, v72
	v_rcp_f32_e32 v73, v73
	v_rcp_f32_e32 v74, v74
	v_mul_f32_e32 v75, 0xbfb8aa3b, v32
	v_cvt_pk_bf16_f32 v72, v67, v72
	v_mul_f32_e32 v67, 0xbfb8aa3b, v38
	v_cvt_pk_bf16_f32 v73, v73, v74
	global_store_dwordx2 v[70:71], v[72:73], off offset:32
	v_mul_f32_e32 v72, 0xbfb8aa3b, v39
	v_mul_f32_e32 v73, 0xbfb8aa3b, v40
	v_mul_f32_e32 v74, 0xbfb8aa3b, v41
	v_exp_f32_e32 v67, v67
	v_exp_f32_e32 v72, v72
	v_exp_f32_e32 v73, v73
	v_exp_f32_e32 v74, v74
	v_add_f32_e32 v67, 1.0, v67
	v_add_f32_e32 v72, 1.0, v72
	v_add_f32_e32 v73, 1.0, v73
	v_add_f32_e32 v74, 1.0, v74
	v_rcp_f32_e32 v67, v67
	v_rcp_f32_e32 v72, v72
	v_rcp_f32_e32 v73, v73
	v_rcp_f32_e32 v74, v74
	v_mul_f32_e32 v76, 0xbfb8aa3b, v33
	v_cvt_pk_bf16_f32 v72, v67, v72
	v_mul_f32_e32 v67, 0xbfb8aa3b, v34
	v_cvt_pk_bf16_f32 v73, v73, v74
	global_store_dwordx2 v[70:71], v[72:73], off offset:64
	v_mul_f32_e32 v72, 0xbfb8aa3b, v35
	v_mul_f32_e32 v73, 0xbfb8aa3b, v36
	v_mul_f32_e32 v74, 0xbfb8aa3b, v37
	v_exp_f32_e32 v67, v67
	v_exp_f32_e32 v72, v72
	v_exp_f32_e32 v73, v73
	v_exp_f32_e32 v74, v74
	v_add_f32_e32 v67, 1.0, v67
	v_add_f32_e32 v72, 1.0, v72
	v_add_f32_e32 v73, 1.0, v73
	v_add_f32_e32 v74, 1.0, v74
	v_rcp_f32_e32 v67, v67
	v_rcp_f32_e32 v72, v72
	v_rcp_f32_e32 v73, v73
	v_rcp_f32_e32 v74, v74
	v_exp_f32_e32 v75, v75
	v_cvt_pk_bf16_f32 v72, v67, v72
	v_mul_f32_e32 v67, 0xbfb8aa3b, v30
	v_cvt_pk_bf16_f32 v73, v73, v74
	v_mul_f32_e32 v74, 0xbfb8aa3b, v31
	v_exp_f32_e32 v67, v67
	v_exp_f32_e32 v74, v74
	v_exp_f32_e32 v76, v76
	global_store_dwordx2 v[70:71], v[72:73], off offset:96
	v_or_b32_e32 v70, 32, v66
	v_ashrrev_i32_e32 v71, 31, v70
	v_lshlrev_b64 v[70:71], 12, v[70:71]
	v_add_f32_e32 v67, 1.0, v67
	v_add_f32_e32 v74, 1.0, v74
	v_add_f32_e32 v75, 1.0, v75
	v_add_f32_e32 v76, 1.0, v76
	v_lshl_add_u64 v[70:71], s[8:9], 0, v[70:71]
	v_rcp_f32_e32 v67, v67
	v_rcp_f32_e32 v74, v74
	v_rcp_f32_e32 v75, v75
	v_rcp_f32_e32 v76, v76
	v_lshl_add_u64 v[70:71], v[70:71], 0, v[0:1]
	v_lshl_add_u64 v[72:73], v[70:71], 0, v[68:69]
	v_lshl_add_u64 v[70:71], v[72:73], 0, s[38:39]
	v_add_co_u32_e32 v72, vcc, s10, v72
	v_cvt_pk_bf16_f32 v74, v67, v74
	v_cvt_pk_bf16_f32 v75, v75, v76
	v_addc_co_u32_e32 v73, vcc, 0, v73, vcc
	global_store_dwordx2 v[72:73], v[74:75], off offset:2048
	v_mul_f32_e32 v67, 0xbfb8aa3b, v26
	v_mul_f32_e32 v72, 0xbfb8aa3b, v27
	v_mul_f32_e32 v73, 0xbfb8aa3b, v28
	v_mul_f32_e32 v74, 0xbfb8aa3b, v29
	v_exp_f32_e32 v67, v67
	v_exp_f32_e32 v72, v72
	v_exp_f32_e32 v73, v73
	v_exp_f32_e32 v74, v74
	v_add_f32_e32 v67, 1.0, v67
	v_add_f32_e32 v72, 1.0, v72
	v_add_f32_e32 v73, 1.0, v73
	v_add_f32_e32 v74, 1.0, v74
	v_rcp_f32_e32 v67, v67
	v_rcp_f32_e32 v72, v72
	v_rcp_f32_e32 v73, v73
	v_rcp_f32_e32 v74, v74
	v_or_b32_e32 v66, 48, v66
	v_cvt_pk_bf16_f32 v72, v67, v72
	v_mul_f32_e32 v67, 0xbfb8aa3b, v22
	v_cvt_pk_bf16_f32 v73, v73, v74
	global_store_dwordx2 v[70:71], v[72:73], off offset:32
	v_mul_f32_e32 v72, 0xbfb8aa3b, v23
	v_mul_f32_e32 v73, 0xbfb8aa3b, v24
	v_mul_f32_e32 v74, 0xbfb8aa3b, v25
	v_exp_f32_e32 v67, v67
	v_exp_f32_e32 v72, v72
	v_exp_f32_e32 v73, v73
	v_exp_f32_e32 v74, v74
	v_add_f32_e32 v67, 1.0, v67
	v_add_f32_e32 v72, 1.0, v72
	v_add_f32_e32 v73, 1.0, v73
	v_add_f32_e32 v74, 1.0, v74
	v_rcp_f32_e32 v67, v67
	v_rcp_f32_e32 v72, v72
	v_rcp_f32_e32 v73, v73
	v_rcp_f32_e32 v74, v74
	v_cvt_pk_bf16_f32 v72, v67, v72
	v_mul_f32_e32 v67, 0xbfb8aa3b, v18
	v_cvt_pk_bf16_f32 v73, v73, v74
	global_store_dwordx2 v[70:71], v[72:73], off offset:64
	v_mul_f32_e32 v72, 0xbfb8aa3b, v19
	v_exp_f32_e32 v67, v67
	v_exp_f32_e32 v72, v72
	v_mul_f32_e32 v73, 0xbfb8aa3b, v20
	v_mul_f32_e32 v74, 0xbfb8aa3b, v21
	v_exp_f32_e32 v73, v73
	v_exp_f32_e32 v74, v74
	v_add_f32_e32 v67, 1.0, v67
	v_add_f32_e32 v72, 1.0, v72
	v_rcp_f32_e32 v67, v67
	v_rcp_f32_e32 v72, v72
	v_add_f32_e32 v73, 1.0, v73
	v_add_f32_e32 v74, 1.0, v74
	v_rcp_f32_e32 v73, v73
	v_rcp_f32_e32 v74, v74
	v_cvt_pk_bf16_f32 v72, v67, v72
	v_ashrrev_i32_e32 v67, 31, v66
	v_lshlrev_b64 v[66:67], 12, v[66:67]
	v_cvt_pk_bf16_f32 v73, v73, v74
	v_lshl_add_u64 v[66:67], s[8:9], 0, v[66:67]
	global_store_dwordx2 v[70:71], v[72:73], off offset:96
	v_lshl_add_u64 v[66:67], v[66:67], 0, v[0:1]
	v_mul_f32_e32 v0, 0xbfb8aa3b, v14
	v_mul_f32_e32 v70, 0xbfb8aa3b, v15
	v_mul_f32_e32 v71, 0xbfb8aa3b, v16
	v_mul_f32_e32 v72, 0xbfb8aa3b, v17
	v_exp_f32_e32 v0, v0
	v_exp_f32_e32 v70, v70
	v_exp_f32_e32 v71, v71
	v_exp_f32_e32 v72, v72
	v_add_f32_e32 v0, 1.0, v0
	v_add_f32_e32 v70, 1.0, v70
	v_add_f32_e32 v71, 1.0, v71
	v_add_f32_e32 v72, 1.0, v72
	v_rcp_f32_e32 v0, v0
	v_rcp_f32_e32 v70, v70
	v_rcp_f32_e32 v71, v71
	v_rcp_f32_e32 v72, v72
	v_lshl_add_u64 v[68:69], v[66:67], 0, v[68:69]
	v_lshl_add_u64 v[66:67], v[68:69], 0, s[38:39]
	v_add_co_u32_e32 v68, vcc, s10, v68
	v_cvt_pk_bf16_f32 v70, v0, v70
	v_cvt_pk_bf16_f32 v71, v71, v72
	v_addc_co_u32_e32 v69, vcc, 0, v69, vcc
	global_store_dwordx2 v[68:69], v[70:71], off offset:2048
	v_mul_f32_e32 v0, 0xbfb8aa3b, v10
	v_mul_f32_e32 v68, 0xbfb8aa3b, v11
	v_mul_f32_e32 v69, 0xbfb8aa3b, v12
	v_mul_f32_e32 v70, 0xbfb8aa3b, v13
	v_exp_f32_e32 v0, v0
	v_exp_f32_e32 v68, v68
	v_exp_f32_e32 v69, v69
	v_exp_f32_e32 v70, v70
	v_add_f32_e32 v0, 1.0, v0
	v_add_f32_e32 v68, 1.0, v68
	v_add_f32_e32 v69, 1.0, v69
	v_add_f32_e32 v70, 1.0, v70
	v_rcp_f32_e32 v0, v0
	v_rcp_f32_e32 v68, v68
	v_rcp_f32_e32 v69, v69
	v_rcp_f32_e32 v70, v70
	s_mov_b64 s[8:9], 0
	v_cvt_pk_bf16_f32 v68, v0, v68
	v_mul_f32_e32 v0, 0xbfb8aa3b, v6
	v_cvt_pk_bf16_f32 v69, v69, v70
	global_store_dwordx2 v[66:67], v[68:69], off offset:32
	v_mul_f32_e32 v68, 0xbfb8aa3b, v7
	v_mul_f32_e32 v69, 0xbfb8aa3b, v8
	v_mul_f32_e32 v70, 0xbfb8aa3b, v9
	v_exp_f32_e32 v0, v0
	v_exp_f32_e32 v68, v68
	v_exp_f32_e32 v69, v69
	v_exp_f32_e32 v70, v70
	v_add_f32_e32 v0, 1.0, v0
	v_add_f32_e32 v68, 1.0, v68
	v_add_f32_e32 v69, 1.0, v69
	v_add_f32_e32 v70, 1.0, v70
	v_rcp_f32_e32 v0, v0
	v_rcp_f32_e32 v68, v68
	v_rcp_f32_e32 v69, v69
	v_rcp_f32_e32 v70, v70
	v_cvt_pk_bf16_f32 v68, v0, v68
	v_mul_f32_e32 v0, 0xbfb8aa3b, v2
	v_cvt_pk_bf16_f32 v69, v69, v70
	global_store_dwordx2 v[66:67], v[68:69], off offset:64
	v_mul_f32_e32 v68, 0xbfb8aa3b, v3
	v_mul_f32_e32 v69, 0xbfb8aa3b, v4
	v_mul_f32_e32 v70, 0xbfb8aa3b, v5
	v_exp_f32_e32 v0, v0
	v_exp_f32_e32 v68, v68
	v_exp_f32_e32 v69, v69
	v_exp_f32_e32 v70, v70
	v_add_f32_e32 v0, 1.0, v0
	v_add_f32_e32 v68, 1.0, v68
	v_add_f32_e32 v69, 1.0, v69
	v_add_f32_e32 v70, 1.0, v70
	v_rcp_f32_e32 v0, v0
	v_rcp_f32_e32 v68, v68
	v_rcp_f32_e32 v69, v69
	v_rcp_f32_e32 v70, v70
	v_cvt_pk_bf16_f32 v68, v0, v68
	v_cvt_pk_bf16_f32 v69, v69, v70
	global_store_dwordx2 v[66:67], v[68:69], off offset:96
